# FF1 SwiGLU epilogue hand-written: packed scale/+1, software-pipelined trans/VALU interleave, saddr stores (bit-identical math)
# baseline (speedup 1.0000x reference)
; __device__ __forceinline__ unsigned pk2(float lo, float hi) { f32x2 v = {lo, hi}; bf16x2_t b = __builtin_convertvector(v, bf16x2_t); return __builtin_bit_cast(unsigned, b); }
; __device__ __forceinline__ float silu_f(float a) { return a * __builtin_amdgcn_rcpf(1.0f + __expf(-a)); }
;     __device__ __forceinline__ void operator()(const f32x4 (&acc)[2][2][4][2], const Unit& u, int wr, int wc, int fr, int fq) const {
;         const int row0 = u.pm * BM + wr * 64 + fr; const int col0 = u.pn * HALF + wc * 32 + 8 * fq;
; #pragma unroll
;         for (int ai = 0; ai < 2; ++ai)
; #pragma unroll
;             for (int m = 0; m < 4; ++m) { const int row = row0 + ai * HALF + m * 16;
;                 const f32x4 a0 = acc[ai][0][m][0], a1 = acc[ai][0][m][1], b0 = acc[ai][1][m][0], b1 = acc[ai][1][m][1];
;                 u32x4 w; w.x = pk2(silu_f(a0[0]) * b0[0], silu_f(a0[1]) * b0[1]); w.y = pk2(silu_f(a0[2]) * b0[2], silu_f(a0[3]) * b0[3]);
;                 w.z = pk2(silu_f(a1[0]) * b1[0], silu_f(a1[1]) * b1[1]); w.w = pk2(silu_f(a1[2]) * b1[2], silu_f(a1[3]) * b1[3]);
;                 *(u32x4*)(H + (size_t)row * ldh + col0) = w; }
.LBB0_717:
	s_mov_b32 s77, 1
	s_andn2_b64 vcc, exec, s[0:1]
	s_mov_b64 s[0:1], -1
	s_mov_b32 s86, 0xbfb8aa3b
	v_lshl_or_b32 v154, s71, 7, v146
	v_lshl_add_u32 v150, s38, 8, v144
	v_lshlrev_b32_e32 v154, 1, v154
	v_mad_u32_u24 v229, v150, s70, v154
	v_pk_mul_f32 v[230:231], v[124:125], s[86:87] op_sel_hi:[1,0]
	v_pk_mul_f32 v[232:233], v[126:127], s[86:87] op_sel_hi:[1,0]
	v_pk_mul_f32 v[234:235], v[116:117], s[86:87] op_sel_hi:[1,0]
	v_pk_mul_f32 v[236:237], v[118:119], s[86:87] op_sel_hi:[1,0]
	v_exp_f32_e32 v230, v230
	v_exp_f32_e32 v231, v231
	v_exp_f32_e32 v232, v232
	v_exp_f32_e32 v233, v233
	v_exp_f32_e32 v234, v234
	v_exp_f32_e32 v235, v235
	v_exp_f32_e32 v236, v236
	v_exp_f32_e32 v237, v237
	v_pk_add_f32 v[230:231], v[230:231], 1.0 op_sel_hi:[1,0]
	v_pk_add_f32 v[232:233], v[232:233], 1.0 op_sel_hi:[1,0]
	v_pk_add_f32 v[234:235], v[234:235], 1.0 op_sel_hi:[1,0]
	v_pk_add_f32 v[236:237], v[236:237], 1.0 op_sel_hi:[1,0]
	v_rcp_f32_e32 v230, v230
	v_pk_mul_f32 v[246:247], v[108:109], s[86:87] op_sel_hi:[1,0]
	v_rcp_f32_e32 v231, v231
	v_pk_mul_f32 v[248:249], v[110:111], s[86:87] op_sel_hi:[1,0]
	v_rcp_f32_e32 v232, v232
	v_pk_mul_f32 v[250:251], v[100:101], s[86:87] op_sel_hi:[1,0]
	v_rcp_f32_e32 v233, v233
	v_pk_mul_f32 v[252:253], v[102:103], s[86:87] op_sel_hi:[1,0]
	v_rcp_f32_e32 v234, v234
	v_rcp_f32_e32 v235, v235
	v_rcp_f32_e32 v236, v236
	v_rcp_f32_e32 v237, v237
	v_exp_f32_e32 v246, v246
	v_pk_mul_f32 v[124:125], v[124:125], v[230:231]
	v_exp_f32_e32 v247, v247
	v_pk_mul_f32 v[126:127], v[126:127], v[232:233]
	v_exp_f32_e32 v248, v248
	v_pk_mul_f32 v[116:117], v[116:117], v[234:235]
	v_exp_f32_e32 v249, v249
	v_pk_mul_f32 v[118:119], v[118:119], v[236:237]
	v_exp_f32_e32 v250, v250
	v_pk_mul_f32 v[124:125], v[124:125], v[120:121]
	v_exp_f32_e32 v251, v251
	v_pk_mul_f32 v[126:127], v[126:127], v[122:123]
	v_exp_f32_e32 v252, v252
	v_pk_mul_f32 v[116:117], v[116:117], v[112:113]
	v_exp_f32_e32 v253, v253
	v_pk_mul_f32 v[118:119], v[118:119], v[114:115]
	v_pk_add_f32 v[246:247], v[246:247], 1.0 op_sel_hi:[1,0]
	v_cvt_pk_bf16_f32 v238, v124, v125
	v_pk_add_f32 v[248:249], v[248:249], 1.0 op_sel_hi:[1,0]
	v_cvt_pk_bf16_f32 v239, v126, v127
	v_pk_add_f32 v[250:251], v[250:251], 1.0 op_sel_hi:[1,0]
	v_cvt_pk_bf16_f32 v240, v116, v117
	v_pk_add_f32 v[252:253], v[252:253], 1.0 op_sel_hi:[1,0]
	v_cvt_pk_bf16_f32 v241, v118, v119
	s_add_u32 s88, s8, 0x0
	s_addc_u32 s89, s9, 0
	global_store_dwordx4 v229, v[238:241], s[88:89]
	v_rcp_f32_e32 v246, v246
	v_pk_mul_f32 v[230:231], v[92:93], s[86:87] op_sel_hi:[1,0]
	v_rcp_f32_e32 v247, v247
	v_pk_mul_f32 v[232:233], v[94:95], s[86:87] op_sel_hi:[1,0]
	v_rcp_f32_e32 v248, v248
	v_pk_mul_f32 v[234:235], v[84:85], s[86:87] op_sel_hi:[1,0]
	v_rcp_f32_e32 v249, v249
	v_pk_mul_f32 v[236:237], v[86:87], s[86:87] op_sel_hi:[1,0]
	v_rcp_f32_e32 v250, v250
	v_rcp_f32_e32 v251, v251
	v_rcp_f32_e32 v252, v252
	v_rcp_f32_e32 v253, v253
	v_exp_f32_e32 v230, v230
	v_pk_mul_f32 v[108:109], v[108:109], v[246:247]
	v_exp_f32_e32 v231, v231
	v_pk_mul_f32 v[110:111], v[110:111], v[248:249]
	v_exp_f32_e32 v232, v232
	v_pk_mul_f32 v[100:101], v[100:101], v[250:251]
	v_exp_f32_e32 v233, v233
	v_pk_mul_f32 v[102:103], v[102:103], v[252:253]
	v_exp_f32_e32 v234, v234
	v_pk_mul_f32 v[108:109], v[108:109], v[104:105]
	v_exp_f32_e32 v235, v235
	v_pk_mul_f32 v[110:111], v[110:111], v[106:107]
	v_exp_f32_e32 v236, v236
	v_pk_mul_f32 v[100:101], v[100:101], v[96:97]
	v_exp_f32_e32 v237, v237
	v_pk_mul_f32 v[102:103], v[102:103], v[98:99]
	v_pk_add_f32 v[230:231], v[230:231], 1.0 op_sel_hi:[1,0]
	v_cvt_pk_bf16_f32 v242, v108, v109
	v_pk_add_f32 v[232:233], v[232:233], 1.0 op_sel_hi:[1,0]
	v_cvt_pk_bf16_f32 v243, v110, v111
	v_pk_add_f32 v[234:235], v[234:235], 1.0 op_sel_hi:[1,0]
	v_cvt_pk_bf16_f32 v244, v100, v101
	v_pk_add_f32 v[236:237], v[236:237], 1.0 op_sel_hi:[1,0]
	v_cvt_pk_bf16_f32 v245, v102, v103
	s_add_u32 s88, s8, 0x16000
	s_addc_u32 s89, s9, 0
	global_store_dwordx4 v229, v[242:245], s[88:89]
	v_rcp_f32_e32 v230, v230
	v_pk_mul_f32 v[246:247], v[76:77], s[86:87] op_sel_hi:[1,0]
	v_rcp_f32_e32 v231, v231
	v_pk_mul_f32 v[248:249], v[78:79], s[86:87] op_sel_hi:[1,0]
	v_rcp_f32_e32 v232, v232
	v_pk_mul_f32 v[250:251], v[68:69], s[86:87] op_sel_hi:[1,0]
	v_rcp_f32_e32 v233, v233
	v_pk_mul_f32 v[252:253], v[70:71], s[86:87] op_sel_hi:[1,0]
	v_rcp_f32_e32 v234, v234
	v_rcp_f32_e32 v235, v235
	v_rcp_f32_e32 v236, v236
	v_rcp_f32_e32 v237, v237
	v_exp_f32_e32 v246, v246
	v_pk_mul_f32 v[92:93], v[92:93], v[230:231]
	v_exp_f32_e32 v247, v247
	v_pk_mul_f32 v[94:95], v[94:95], v[232:233]
	v_exp_f32_e32 v248, v248
	v_pk_mul_f32 v[84:85], v[84:85], v[234:235]
	v_exp_f32_e32 v249, v249
	v_pk_mul_f32 v[86:87], v[86:87], v[236:237]
	v_exp_f32_e32 v250, v250
	v_pk_mul_f32 v[92:93], v[92:93], v[88:89]
	v_exp_f32_e32 v251, v251
	v_pk_mul_f32 v[94:95], v[94:95], v[90:91]
	v_exp_f32_e32 v252, v252
	v_pk_mul_f32 v[84:85], v[84:85], v[80:81]
	v_exp_f32_e32 v253, v253
	v_pk_mul_f32 v[86:87], v[86:87], v[82:83]
	v_pk_add_f32 v[246:247], v[246:247], 1.0 op_sel_hi:[1,0]
	v_cvt_pk_bf16_f32 v238, v92, v93
	v_pk_add_f32 v[248:249], v[248:249], 1.0 op_sel_hi:[1,0]
	v_cvt_pk_bf16_f32 v239, v94, v95
	v_pk_add_f32 v[250:251], v[250:251], 1.0 op_sel_hi:[1,0]
	v_cvt_pk_bf16_f32 v240, v84, v85
	v_pk_add_f32 v[252:253], v[252:253], 1.0 op_sel_hi:[1,0]
	v_cvt_pk_bf16_f32 v241, v86, v87
	s_add_u32 s88, s8, 0x2c000
	s_addc_u32 s89, s9, 0
	global_store_dwordx4 v229, v[238:241], s[88:89]
	v_rcp_f32_e32 v246, v246
	v_pk_mul_f32 v[230:231], v[60:61], s[86:87] op_sel_hi:[1,0]
	v_rcp_f32_e32 v247, v247
	v_pk_mul_f32 v[232:233], v[62:63], s[86:87] op_sel_hi:[1,0]
; __device__ __forceinline__ unsigned pk2(float lo, float hi) { f32x2 v = {lo, hi}; bf16x2_t b = __builtin_convertvector(v, bf16x2_t); return __builtin_bit_cast(unsigned, b); }
; __device__ __forceinline__ float silu_f(float a) { return a * __builtin_amdgcn_rcpf(1.0f + __expf(-a)); }
;     __device__ __forceinline__ void operator()(const f32x4 (&acc)[2][2][4][2], const Unit& u, int wr, int wc, int fr, int fq) const {
;         const int row0 = u.pm * BM + wr * 64 + fr; const int col0 = u.pn * HALF + wc * 32 + 8 * fq;
; #pragma unroll
;         for (int ai = 0; ai < 2; ++ai)
; #pragma unroll
;             for (int m = 0; m < 4; ++m) { const int row = row0 + ai * HALF + m * 16;
;                 const f32x4 a0 = acc[ai][0][m][0], a1 = acc[ai][0][m][1], b0 = acc[ai][1][m][0], b1 = acc[ai][1][m][1];
;                 u32x4 w; w.x = pk2(silu_f(a0[0]) * b0[0], silu_f(a0[1]) * b0[1]); w.y = pk2(silu_f(a0[2]) * b0[2], silu_f(a0[3]) * b0[3]);
;                 w.z = pk2(silu_f(a1[0]) * b1[0], silu_f(a1[1]) * b1[1]); w.w = pk2(silu_f(a1[2]) * b1[2], silu_f(a1[3]) * b1[3]);
;                 *(u32x4*)(H + (size_t)row * ldh + col0) = w; }
	v_rcp_f32_e32 v248, v248
	v_pk_mul_f32 v[234:235], v[52:53], s[86:87] op_sel_hi:[1,0]
	v_rcp_f32_e32 v249, v249
	v_pk_mul_f32 v[236:237], v[54:55], s[86:87] op_sel_hi:[1,0]
	v_rcp_f32_e32 v250, v250
	v_rcp_f32_e32 v251, v251
	v_rcp_f32_e32 v252, v252
	v_rcp_f32_e32 v253, v253
	v_exp_f32_e32 v230, v230
	v_pk_mul_f32 v[76:77], v[76:77], v[246:247]
	v_exp_f32_e32 v231, v231
	v_pk_mul_f32 v[78:79], v[78:79], v[248:249]
	v_exp_f32_e32 v232, v232
	v_pk_mul_f32 v[68:69], v[68:69], v[250:251]
	v_exp_f32_e32 v233, v233
	v_pk_mul_f32 v[70:71], v[70:71], v[252:253]
	v_exp_f32_e32 v234, v234
	v_pk_mul_f32 v[76:77], v[76:77], v[72:73]
	v_exp_f32_e32 v235, v235
	v_pk_mul_f32 v[78:79], v[78:79], v[74:75]
	v_exp_f32_e32 v236, v236
	v_pk_mul_f32 v[68:69], v[68:69], v[64:65]
	v_exp_f32_e32 v237, v237
	v_pk_mul_f32 v[70:71], v[70:71], v[66:67]
	v_pk_add_f32 v[230:231], v[230:231], 1.0 op_sel_hi:[1,0]
	v_cvt_pk_bf16_f32 v242, v76, v77
	v_pk_add_f32 v[232:233], v[232:233], 1.0 op_sel_hi:[1,0]
	v_cvt_pk_bf16_f32 v243, v78, v79
	v_pk_add_f32 v[234:235], v[234:235], 1.0 op_sel_hi:[1,0]
	v_cvt_pk_bf16_f32 v244, v68, v69
	v_pk_add_f32 v[236:237], v[236:237], 1.0 op_sel_hi:[1,0]
	v_cvt_pk_bf16_f32 v245, v70, v71
	s_add_u32 s88, s8, 0x42000
	s_addc_u32 s89, s9, 0
	global_store_dwordx4 v229, v[242:245], s[88:89]
	v_rcp_f32_e32 v230, v230
	v_pk_mul_f32 v[246:247], v[44:45], s[86:87] op_sel_hi:[1,0]
	v_rcp_f32_e32 v231, v231
	v_pk_mul_f32 v[248:249], v[46:47], s[86:87] op_sel_hi:[1,0]
	v_rcp_f32_e32 v232, v232
	v_pk_mul_f32 v[250:251], v[36:37], s[86:87] op_sel_hi:[1,0]
	v_rcp_f32_e32 v233, v233
	v_pk_mul_f32 v[252:253], v[38:39], s[86:87] op_sel_hi:[1,0]
	v_rcp_f32_e32 v234, v234
	v_rcp_f32_e32 v235, v235
	v_rcp_f32_e32 v236, v236
	v_rcp_f32_e32 v237, v237
	v_exp_f32_e32 v246, v246
	v_pk_mul_f32 v[60:61], v[60:61], v[230:231]
	v_exp_f32_e32 v247, v247
	v_pk_mul_f32 v[62:63], v[62:63], v[232:233]
	v_exp_f32_e32 v248, v248
	v_pk_mul_f32 v[52:53], v[52:53], v[234:235]
	v_exp_f32_e32 v249, v249
	v_pk_mul_f32 v[54:55], v[54:55], v[236:237]
	v_exp_f32_e32 v250, v250
	v_pk_mul_f32 v[60:61], v[60:61], v[56:57]
	v_exp_f32_e32 v251, v251
	v_pk_mul_f32 v[62:63], v[62:63], v[58:59]
	v_exp_f32_e32 v252, v252
	v_pk_mul_f32 v[52:53], v[52:53], v[48:49]
	v_exp_f32_e32 v253, v253
	v_pk_mul_f32 v[54:55], v[54:55], v[50:51]
	v_pk_add_f32 v[246:247], v[246:247], 1.0 op_sel_hi:[1,0]
	v_cvt_pk_bf16_f32 v238, v60, v61
	v_pk_add_f32 v[248:249], v[248:249], 1.0 op_sel_hi:[1,0]
	v_cvt_pk_bf16_f32 v239, v62, v63
	v_pk_add_f32 v[250:251], v[250:251], 1.0 op_sel_hi:[1,0]
	v_cvt_pk_bf16_f32 v240, v52, v53
	v_pk_add_f32 v[252:253], v[252:253], 1.0 op_sel_hi:[1,0]
	v_cvt_pk_bf16_f32 v241, v54, v55
	s_add_u32 s88, s8, 0xb0000
	s_addc_u32 s89, s9, 0
	global_store_dwordx4 v229, v[238:241], s[88:89]
	v_rcp_f32_e32 v246, v246
	v_pk_mul_f32 v[230:231], v[28:29], s[86:87] op_sel_hi:[1,0]
	v_rcp_f32_e32 v247, v247
	v_pk_mul_f32 v[232:233], v[30:31], s[86:87] op_sel_hi:[1,0]
	v_rcp_f32_e32 v248, v248
	v_pk_mul_f32 v[234:235], v[20:21], s[86:87] op_sel_hi:[1,0]
	v_rcp_f32_e32 v249, v249
	v_pk_mul_f32 v[236:237], v[22:23], s[86:87] op_sel_hi:[1,0]
	v_rcp_f32_e32 v250, v250
	v_rcp_f32_e32 v251, v251
	v_rcp_f32_e32 v252, v252
	v_rcp_f32_e32 v253, v253
	v_exp_f32_e32 v230, v230
	v_pk_mul_f32 v[44:45], v[44:45], v[246:247]
	v_exp_f32_e32 v231, v231
	v_pk_mul_f32 v[46:47], v[46:47], v[248:249]
	v_exp_f32_e32 v232, v232
	v_pk_mul_f32 v[36:37], v[36:37], v[250:251]
	v_exp_f32_e32 v233, v233
	v_pk_mul_f32 v[38:39], v[38:39], v[252:253]
	v_exp_f32_e32 v234, v234
	v_pk_mul_f32 v[44:45], v[44:45], v[40:41]
	v_exp_f32_e32 v235, v235
	v_pk_mul_f32 v[46:47], v[46:47], v[42:43]
	v_exp_f32_e32 v236, v236
	v_pk_mul_f32 v[36:37], v[36:37], v[32:33]
	v_exp_f32_e32 v237, v237
	v_pk_mul_f32 v[38:39], v[38:39], v[34:35]
	v_pk_add_f32 v[230:231], v[230:231], 1.0 op_sel_hi:[1,0]
	v_cvt_pk_bf16_f32 v242, v44, v45
	v_pk_add_f32 v[232:233], v[232:233], 1.0 op_sel_hi:[1,0]
	v_cvt_pk_bf16_f32 v243, v46, v47
	v_pk_add_f32 v[234:235], v[234:235], 1.0 op_sel_hi:[1,0]
	v_cvt_pk_bf16_f32 v244, v36, v37
	v_pk_add_f32 v[236:237], v[236:237], 1.0 op_sel_hi:[1,0]
	v_cvt_pk_bf16_f32 v245, v38, v39
	s_add_u32 s88, s8, 0xc6000
	s_addc_u32 s89, s9, 0
	global_store_dwordx4 v229, v[242:245], s[88:89]
	v_rcp_f32_e32 v230, v230
	v_pk_mul_f32 v[246:247], v[12:13], s[86:87] op_sel_hi:[1,0]
	v_rcp_f32_e32 v231, v231
	v_pk_mul_f32 v[248:249], v[14:15], s[86:87] op_sel_hi:[1,0]
	v_rcp_f32_e32 v232, v232
	v_pk_mul_f32 v[250:251], v[4:5], s[86:87] op_sel_hi:[1,0]
	v_rcp_f32_e32 v233, v233
	v_pk_mul_f32 v[252:253], v[6:7], s[86:87] op_sel_hi:[1,0]
	v_rcp_f32_e32 v234, v234
	v_rcp_f32_e32 v235, v235
	v_rcp_f32_e32 v236, v236
	v_rcp_f32_e32 v237, v237
	v_exp_f32_e32 v246, v246
	v_pk_mul_f32 v[28:29], v[28:29], v[230:231]
	v_exp_f32_e32 v247, v247
	v_pk_mul_f32 v[30:31], v[30:31], v[232:233]
	v_exp_f32_e32 v248, v248
	v_pk_mul_f32 v[20:21], v[20:21], v[234:235]
	v_exp_f32_e32 v249, v249
	v_pk_mul_f32 v[22:23], v[22:23], v[236:237]
	v_exp_f32_e32 v250, v250
	v_pk_mul_f32 v[28:29], v[28:29], v[24:25]
	v_exp_f32_e32 v251, v251
	v_pk_mul_f32 v[30:31], v[30:31], v[26:27]
	v_exp_f32_e32 v252, v252
	v_pk_mul_f32 v[20:21], v[20:21], v[16:17]
	v_exp_f32_e32 v253, v253
	v_pk_mul_f32 v[22:23], v[22:23], v[18:19]
	v_pk_add_f32 v[246:247], v[246:247], 1.0 op_sel_hi:[1,0]
	v_cvt_pk_bf16_f32 v238, v28, v29
	v_pk_add_f32 v[248:249], v[248:249], 1.0 op_sel_hi:[1,0]
	v_cvt_pk_bf16_f32 v239, v30, v31
	v_pk_add_f32 v[250:251], v[250:251], 1.0 op_sel_hi:[1,0]
	v_cvt_pk_bf16_f32 v240, v20, v21
	v_pk_add_f32 v[252:253], v[252:253], 1.0 op_sel_hi:[1,0]
	v_cvt_pk_bf16_f32 v241, v22, v23
	s_add_u32 s88, s8, 0xdc000
	s_addc_u32 s89, s9, 0
	global_store_dwordx4 v229, v[238:241], s[88:89]
	v_rcp_f32_e32 v246, v246
	v_rcp_f32_e32 v247, v247
	v_rcp_f32_e32 v248, v248
	v_rcp_f32_e32 v249, v249
	v_rcp_f32_e32 v250, v250
	v_rcp_f32_e32 v251, v251
	v_rcp_f32_e32 v252, v252
	v_rcp_f32_e32 v253, v253
	v_pk_mul_f32 v[12:13], v[12:13], v[246:247]
	v_pk_mul_f32 v[14:15], v[14:15], v[248:249]
	v_pk_mul_f32 v[4:5], v[4:5], v[250:251]
	v_pk_mul_f32 v[6:7], v[6:7], v[252:253]
	v_pk_mul_f32 v[12:13], v[12:13], v[8:9]
	v_pk_mul_f32 v[14:15], v[14:15], v[10:11]
	v_pk_mul_f32 v[4:5], v[4:5], v[0:1]
	v_pk_mul_f32 v[6:7], v[6:7], v[2:3]
	v_cvt_pk_bf16_f32 v242, v12, v13
	v_cvt_pk_bf16_f32 v243, v14, v15
	v_cvt_pk_bf16_f32 v244, v4, v5
	v_cvt_pk_bf16_f32 v245, v6, v7
	s_add_u32 s88, s8, 0xf2000
	s_addc_u32 s89, s9, 0
	global_store_dwordx4 v229, v[242:245], s[88:89]
	s_cbranch_vccnz .LBB0_710
	s_andn2_b64 vcc, exec, s[6:7]
	s_cbranch_vccnz .LBB0_709
	s_barrier
	s_branch .LBB0_709

; __device__ __forceinline__ unsigned pk2(float lo, float hi) { f32x2 v = {lo, hi}; bf16x2_t b = __builtin_convertvector(v, bf16x2_t); return __builtin_bit_cast(unsigned, b); }
; __device__ __forceinline__ float silu_f(float a) { return a * __builtin_amdgcn_rcpf(1.0f + __expf(-a)); }
;     __device__ __forceinline__ void operator()(const f32x4 (&acc)[2][2][4][2], const Unit& u, int wr, int wc, int fr, int fq) const {
;         const int row0 = u.pm * BM + wr * 64 + fr; const int col0 = u.pn * HALF + wc * 32 + 8 * fq;
; #pragma unroll
;         for (int ai = 0; ai < 2; ++ai)
; #pragma unroll
;             for (int m = 0; m < 4; ++m) { const int row = row0 + ai * HALF + m * 16;
;                 const f32x4 a0 = acc[ai][0][m][0], a1 = acc[ai][0][m][1], b0 = acc[ai][1][m][0], b1 = acc[ai][1][m][1];
;                 u32x4 w; w.x = pk2(silu_f(a0[0]) * b0[0], silu_f(a0[1]) * b0[1]); w.y = pk2(silu_f(a0[2]) * b0[2], silu_f(a0[3]) * b0[3]);
;                 w.z = pk2(silu_f(a1[0]) * b1[0], silu_f(a1[1]) * b1[1]); w.w = pk2(silu_f(a1[2]) * b1[2], silu_f(a1[3]) * b1[3]);
;                 *(u32x4*)(H + (size_t)row * ldh + col0) = w; }
.LBB0_1345:
	s_mov_b32 s77, 1
	s_andn2_b64 vcc, exec, s[0:1]
	s_mov_b64 s[0:1], -1
	s_mov_b32 s86, 0xbfb8aa3b
	v_lshl_or_b32 v154, s57, 7, v146
	v_lshl_add_u32 v150, s24, 8, v144
	v_lshlrev_b32_e32 v154, 1, v154
	v_mad_u32_u24 v229, v150, s56, v154
	v_pk_mul_f32 v[230:231], v[124:125], s[86:87] op_sel_hi:[1,0]
	v_pk_mul_f32 v[232:233], v[126:127], s[86:87] op_sel_hi:[1,0]
	v_pk_mul_f32 v[234:235], v[116:117], s[86:87] op_sel_hi:[1,0]
	v_pk_mul_f32 v[236:237], v[118:119], s[86:87] op_sel_hi:[1,0]
	v_exp_f32_e32 v230, v230
	v_exp_f32_e32 v231, v231
	v_exp_f32_e32 v232, v232
	v_exp_f32_e32 v233, v233
	v_exp_f32_e32 v234, v234
	v_exp_f32_e32 v235, v235
	v_exp_f32_e32 v236, v236
	v_exp_f32_e32 v237, v237
	v_pk_add_f32 v[230:231], v[230:231], 1.0 op_sel_hi:[1,0]
	v_pk_add_f32 v[232:233], v[232:233], 1.0 op_sel_hi:[1,0]
	v_pk_add_f32 v[234:235], v[234:235], 1.0 op_sel_hi:[1,0]
	v_pk_add_f32 v[236:237], v[236:237], 1.0 op_sel_hi:[1,0]
	v_rcp_f32_e32 v230, v230
	v_pk_mul_f32 v[246:247], v[108:109], s[86:87] op_sel_hi:[1,0]
	v_rcp_f32_e32 v231, v231
	v_pk_mul_f32 v[248:249], v[110:111], s[86:87] op_sel_hi:[1,0]
	v_rcp_f32_e32 v232, v232
	v_pk_mul_f32 v[250:251], v[100:101], s[86:87] op_sel_hi:[1,0]
	v_rcp_f32_e32 v233, v233
	v_pk_mul_f32 v[252:253], v[102:103], s[86:87] op_sel_hi:[1,0]
	v_rcp_f32_e32 v234, v234
	v_rcp_f32_e32 v235, v235
	v_rcp_f32_e32 v236, v236
	v_rcp_f32_e32 v237, v237
	v_exp_f32_e32 v246, v246
	v_pk_mul_f32 v[124:125], v[124:125], v[230:231]
	v_exp_f32_e32 v247, v247
	v_pk_mul_f32 v[126:127], v[126:127], v[232:233]
	v_exp_f32_e32 v248, v248
	v_pk_mul_f32 v[116:117], v[116:117], v[234:235]
	v_exp_f32_e32 v249, v249
	v_pk_mul_f32 v[118:119], v[118:119], v[236:237]
	v_exp_f32_e32 v250, v250
	v_pk_mul_f32 v[124:125], v[124:125], v[120:121]
	v_exp_f32_e32 v251, v251
	v_pk_mul_f32 v[126:127], v[126:127], v[122:123]
	v_exp_f32_e32 v252, v252
	v_pk_mul_f32 v[116:117], v[116:117], v[112:113]
	v_exp_f32_e32 v253, v253
	v_pk_mul_f32 v[118:119], v[118:119], v[114:115]
	v_pk_add_f32 v[246:247], v[246:247], 1.0 op_sel_hi:[1,0]
	v_cvt_pk_bf16_f32 v238, v124, v125
	v_pk_add_f32 v[248:249], v[248:249], 1.0 op_sel_hi:[1,0]
	v_cvt_pk_bf16_f32 v239, v126, v127
	v_pk_add_f32 v[250:251], v[250:251], 1.0 op_sel_hi:[1,0]
	v_cvt_pk_bf16_f32 v240, v116, v117
	v_pk_add_f32 v[252:253], v[252:253], 1.0 op_sel_hi:[1,0]
	v_cvt_pk_bf16_f32 v241, v118, v119
	s_add_u32 s88, s8, 0x0
	s_addc_u32 s89, s9, 0
	global_store_dwordx4 v229, v[238:241], s[88:89]
	v_rcp_f32_e32 v246, v246
	v_pk_mul_f32 v[230:231], v[92:93], s[86:87] op_sel_hi:[1,0]
	v_rcp_f32_e32 v247, v247
	v_pk_mul_f32 v[232:233], v[94:95], s[86:87] op_sel_hi:[1,0]
	v_rcp_f32_e32 v248, v248
	v_pk_mul_f32 v[234:235], v[84:85], s[86:87] op_sel_hi:[1,0]
	v_rcp_f32_e32 v249, v249
	v_pk_mul_f32 v[236:237], v[86:87], s[86:87] op_sel_hi:[1,0]
	v_rcp_f32_e32 v250, v250
	v_rcp_f32_e32 v251, v251
	v_rcp_f32_e32 v252, v252
	v_rcp_f32_e32 v253, v253
	v_exp_f32_e32 v230, v230
	v_pk_mul_f32 v[108:109], v[108:109], v[246:247]
	v_exp_f32_e32 v231, v231
	v_pk_mul_f32 v[110:111], v[110:111], v[248:249]
	v_exp_f32_e32 v232, v232
	v_pk_mul_f32 v[100:101], v[100:101], v[250:251]
	v_exp_f32_e32 v233, v233
	v_pk_mul_f32 v[102:103], v[102:103], v[252:253]
	v_exp_f32_e32 v234, v234
	v_pk_mul_f32 v[108:109], v[108:109], v[104:105]
	v_exp_f32_e32 v235, v235
	v_pk_mul_f32 v[110:111], v[110:111], v[106:107]
	v_exp_f32_e32 v236, v236
	v_pk_mul_f32 v[100:101], v[100:101], v[96:97]
	v_exp_f32_e32 v237, v237
	v_pk_mul_f32 v[102:103], v[102:103], v[98:99]
	v_pk_add_f32 v[230:231], v[230:231], 1.0 op_sel_hi:[1,0]
	v_cvt_pk_bf16_f32 v242, v108, v109
	v_pk_add_f32 v[232:233], v[232:233], 1.0 op_sel_hi:[1,0]
	v_cvt_pk_bf16_f32 v243, v110, v111
	v_pk_add_f32 v[234:235], v[234:235], 1.0 op_sel_hi:[1,0]
	v_cvt_pk_bf16_f32 v244, v100, v101
	v_pk_add_f32 v[236:237], v[236:237], 1.0 op_sel_hi:[1,0]
	v_cvt_pk_bf16_f32 v245, v102, v103
	s_add_u32 s88, s8, 0x16000
	s_addc_u32 s89, s9, 0
	global_store_dwordx4 v229, v[242:245], s[88:89]
	v_rcp_f32_e32 v230, v230
	v_pk_mul_f32 v[246:247], v[76:77], s[86:87] op_sel_hi:[1,0]
	v_rcp_f32_e32 v231, v231
	v_pk_mul_f32 v[248:249], v[78:79], s[86:87] op_sel_hi:[1,0]
	v_rcp_f32_e32 v232, v232
	v_pk_mul_f32 v[250:251], v[68:69], s[86:87] op_sel_hi:[1,0]
	v_rcp_f32_e32 v233, v233
	v_pk_mul_f32 v[252:253], v[70:71], s[86:87] op_sel_hi:[1,0]
	v_rcp_f32_e32 v234, v234
	v_rcp_f32_e32 v235, v235
	v_rcp_f32_e32 v236, v236
	v_rcp_f32_e32 v237, v237
	v_exp_f32_e32 v246, v246
	v_pk_mul_f32 v[92:93], v[92:93], v[230:231]
	v_exp_f32_e32 v247, v247
	v_pk_mul_f32 v[94:95], v[94:95], v[232:233]
	v_exp_f32_e32 v248, v248
	v_pk_mul_f32 v[84:85], v[84:85], v[234:235]
	v_exp_f32_e32 v249, v249
	v_pk_mul_f32 v[86:87], v[86:87], v[236:237]
	v_exp_f32_e32 v250, v250
	v_pk_mul_f32 v[92:93], v[92:93], v[88:89]
	v_exp_f32_e32 v251, v251
	v_pk_mul_f32 v[94:95], v[94:95], v[90:91]
	v_exp_f32_e32 v252, v252
	v_pk_mul_f32 v[84:85], v[84:85], v[80:81]
	v_exp_f32_e32 v253, v253
	v_pk_mul_f32 v[86:87], v[86:87], v[82:83]
	v_pk_add_f32 v[246:247], v[246:247], 1.0 op_sel_hi:[1,0]
	v_cvt_pk_bf16_f32 v238, v92, v93
	v_pk_add_f32 v[248:249], v[248:249], 1.0 op_sel_hi:[1,0]
	v_cvt_pk_bf16_f32 v239, v94, v95
	v_pk_add_f32 v[250:251], v[250:251], 1.0 op_sel_hi:[1,0]
	v_cvt_pk_bf16_f32 v240, v84, v85
	v_pk_add_f32 v[252:253], v[252:253], 1.0 op_sel_hi:[1,0]
	v_cvt_pk_bf16_f32 v241, v86, v87
	s_add_u32 s88, s8, 0x2c000
	s_addc_u32 s89, s9, 0
	global_store_dwordx4 v229, v[238:241], s[88:89]
	v_rcp_f32_e32 v246, v246
	v_pk_mul_f32 v[230:231], v[60:61], s[86:87] op_sel_hi:[1,0]
	v_rcp_f32_e32 v247, v247
	v_pk_mul_f32 v[232:233], v[62:63], s[86:87] op_sel_hi:[1,0]
; __device__ __forceinline__ unsigned pk2(float lo, float hi) { f32x2 v = {lo, hi}; bf16x2_t b = __builtin_convertvector(v, bf16x2_t); return __builtin_bit_cast(unsigned, b); }
; __device__ __forceinline__ float silu_f(float a) { return a * __builtin_amdgcn_rcpf(1.0f + __expf(-a)); }
;     __device__ __forceinline__ void operator()(const f32x4 (&acc)[2][2][4][2], const Unit& u, int wr, int wc, int fr, int fq) const {
;         const int row0 = u.pm * BM + wr * 64 + fr; const int col0 = u.pn * HALF + wc * 32 + 8 * fq;
; #pragma unroll
;         for (int ai = 0; ai < 2; ++ai)
; #pragma unroll
;             for (int m = 0; m < 4; ++m) { const int row = row0 + ai * HALF + m * 16;
;                 const f32x4 a0 = acc[ai][0][m][0], a1 = acc[ai][0][m][1], b0 = acc[ai][1][m][0], b1 = acc[ai][1][m][1];
;                 u32x4 w; w.x = pk2(silu_f(a0[0]) * b0[0], silu_f(a0[1]) * b0[1]); w.y = pk2(silu_f(a0[2]) * b0[2], silu_f(a0[3]) * b0[3]);
;                 w.z = pk2(silu_f(a1[0]) * b1[0], silu_f(a1[1]) * b1[1]); w.w = pk2(silu_f(a1[2]) * b1[2], silu_f(a1[3]) * b1[3]);
;                 *(u32x4*)(H + (size_t)row * ldh + col0) = w; }
	v_rcp_f32_e32 v248, v248
	v_pk_mul_f32 v[234:235], v[52:53], s[86:87] op_sel_hi:[1,0]
	v_rcp_f32_e32 v249, v249
	v_pk_mul_f32 v[236:237], v[54:55], s[86:87] op_sel_hi:[1,0]
	v_rcp_f32_e32 v250, v250
	v_rcp_f32_e32 v251, v251
	v_rcp_f32_e32 v252, v252
	v_rcp_f32_e32 v253, v253
	v_exp_f32_e32 v230, v230
	v_pk_mul_f32 v[76:77], v[76:77], v[246:247]
	v_exp_f32_e32 v231, v231
	v_pk_mul_f32 v[78:79], v[78:79], v[248:249]
	v_exp_f32_e32 v232, v232
	v_pk_mul_f32 v[68:69], v[68:69], v[250:251]
	v_exp_f32_e32 v233, v233
	v_pk_mul_f32 v[70:71], v[70:71], v[252:253]
	v_exp_f32_e32 v234, v234
	v_pk_mul_f32 v[76:77], v[76:77], v[72:73]
	v_exp_f32_e32 v235, v235
	v_pk_mul_f32 v[78:79], v[78:79], v[74:75]
	v_exp_f32_e32 v236, v236
	v_pk_mul_f32 v[68:69], v[68:69], v[64:65]
	v_exp_f32_e32 v237, v237
	v_pk_mul_f32 v[70:71], v[70:71], v[66:67]
	v_pk_add_f32 v[230:231], v[230:231], 1.0 op_sel_hi:[1,0]
	v_cvt_pk_bf16_f32 v242, v76, v77
	v_pk_add_f32 v[232:233], v[232:233], 1.0 op_sel_hi:[1,0]
	v_cvt_pk_bf16_f32 v243, v78, v79
	v_pk_add_f32 v[234:235], v[234:235], 1.0 op_sel_hi:[1,0]
	v_cvt_pk_bf16_f32 v244, v68, v69
	v_pk_add_f32 v[236:237], v[236:237], 1.0 op_sel_hi:[1,0]
	v_cvt_pk_bf16_f32 v245, v70, v71
	s_add_u32 s88, s8, 0x42000
	s_addc_u32 s89, s9, 0
	global_store_dwordx4 v229, v[242:245], s[88:89]
	v_rcp_f32_e32 v230, v230
	v_pk_mul_f32 v[246:247], v[44:45], s[86:87] op_sel_hi:[1,0]
	v_rcp_f32_e32 v231, v231
	v_pk_mul_f32 v[248:249], v[46:47], s[86:87] op_sel_hi:[1,0]
	v_rcp_f32_e32 v232, v232
	v_pk_mul_f32 v[250:251], v[36:37], s[86:87] op_sel_hi:[1,0]
	v_rcp_f32_e32 v233, v233
	v_pk_mul_f32 v[252:253], v[38:39], s[86:87] op_sel_hi:[1,0]
	v_rcp_f32_e32 v234, v234
	v_rcp_f32_e32 v235, v235
	v_rcp_f32_e32 v236, v236
	v_rcp_f32_e32 v237, v237
	v_exp_f32_e32 v246, v246
	v_pk_mul_f32 v[60:61], v[60:61], v[230:231]
	v_exp_f32_e32 v247, v247
	v_pk_mul_f32 v[62:63], v[62:63], v[232:233]
	v_exp_f32_e32 v248, v248
	v_pk_mul_f32 v[52:53], v[52:53], v[234:235]
	v_exp_f32_e32 v249, v249
	v_pk_mul_f32 v[54:55], v[54:55], v[236:237]
	v_exp_f32_e32 v250, v250
	v_pk_mul_f32 v[60:61], v[60:61], v[56:57]
	v_exp_f32_e32 v251, v251
	v_pk_mul_f32 v[62:63], v[62:63], v[58:59]
	v_exp_f32_e32 v252, v252
	v_pk_mul_f32 v[52:53], v[52:53], v[48:49]
	v_exp_f32_e32 v253, v253
	v_pk_mul_f32 v[54:55], v[54:55], v[50:51]
	v_pk_add_f32 v[246:247], v[246:247], 1.0 op_sel_hi:[1,0]
	v_cvt_pk_bf16_f32 v238, v60, v61
	v_pk_add_f32 v[248:249], v[248:249], 1.0 op_sel_hi:[1,0]
	v_cvt_pk_bf16_f32 v239, v62, v63
	v_pk_add_f32 v[250:251], v[250:251], 1.0 op_sel_hi:[1,0]
	v_cvt_pk_bf16_f32 v240, v52, v53
	v_pk_add_f32 v[252:253], v[252:253], 1.0 op_sel_hi:[1,0]
	v_cvt_pk_bf16_f32 v241, v54, v55
	s_add_u32 s88, s8, 0xb0000
	s_addc_u32 s89, s9, 0
	global_store_dwordx4 v229, v[238:241], s[88:89]
	v_rcp_f32_e32 v246, v246
	v_pk_mul_f32 v[230:231], v[28:29], s[86:87] op_sel_hi:[1,0]
	v_rcp_f32_e32 v247, v247
	v_pk_mul_f32 v[232:233], v[30:31], s[86:87] op_sel_hi:[1,0]
	v_rcp_f32_e32 v248, v248
	v_pk_mul_f32 v[234:235], v[20:21], s[86:87] op_sel_hi:[1,0]
	v_rcp_f32_e32 v249, v249
	v_pk_mul_f32 v[236:237], v[22:23], s[86:87] op_sel_hi:[1,0]
	v_rcp_f32_e32 v250, v250
	v_rcp_f32_e32 v251, v251
	v_rcp_f32_e32 v252, v252
	v_rcp_f32_e32 v253, v253
	v_exp_f32_e32 v230, v230
	v_pk_mul_f32 v[44:45], v[44:45], v[246:247]
	v_exp_f32_e32 v231, v231
	v_pk_mul_f32 v[46:47], v[46:47], v[248:249]
	v_exp_f32_e32 v232, v232
	v_pk_mul_f32 v[36:37], v[36:37], v[250:251]
	v_exp_f32_e32 v233, v233
	v_pk_mul_f32 v[38:39], v[38:39], v[252:253]
	v_exp_f32_e32 v234, v234
	v_pk_mul_f32 v[44:45], v[44:45], v[40:41]
	v_exp_f32_e32 v235, v235
	v_pk_mul_f32 v[46:47], v[46:47], v[42:43]
	v_exp_f32_e32 v236, v236
	v_pk_mul_f32 v[36:37], v[36:37], v[32:33]
	v_exp_f32_e32 v237, v237
	v_pk_mul_f32 v[38:39], v[38:39], v[34:35]
	v_pk_add_f32 v[230:231], v[230:231], 1.0 op_sel_hi:[1,0]
	v_cvt_pk_bf16_f32 v242, v44, v45
	v_pk_add_f32 v[232:233], v[232:233], 1.0 op_sel_hi:[1,0]
	v_cvt_pk_bf16_f32 v243, v46, v47
	v_pk_add_f32 v[234:235], v[234:235], 1.0 op_sel_hi:[1,0]
	v_cvt_pk_bf16_f32 v244, v36, v37
	v_pk_add_f32 v[236:237], v[236:237], 1.0 op_sel_hi:[1,0]
	v_cvt_pk_bf16_f32 v245, v38, v39
	s_add_u32 s88, s8, 0xc6000
	s_addc_u32 s89, s9, 0
	global_store_dwordx4 v229, v[242:245], s[88:89]
	v_rcp_f32_e32 v230, v230
	v_pk_mul_f32 v[246:247], v[12:13], s[86:87] op_sel_hi:[1,0]
	v_rcp_f32_e32 v231, v231
	v_pk_mul_f32 v[248:249], v[14:15], s[86:87] op_sel_hi:[1,0]
	v_rcp_f32_e32 v232, v232
	v_pk_mul_f32 v[250:251], v[4:5], s[86:87] op_sel_hi:[1,0]
	v_rcp_f32_e32 v233, v233
	v_pk_mul_f32 v[252:253], v[6:7], s[86:87] op_sel_hi:[1,0]
	v_rcp_f32_e32 v234, v234
	v_rcp_f32_e32 v235, v235
	v_rcp_f32_e32 v236, v236
	v_rcp_f32_e32 v237, v237
	v_exp_f32_e32 v246, v246
	v_pk_mul_f32 v[28:29], v[28:29], v[230:231]
	v_exp_f32_e32 v247, v247
	v_pk_mul_f32 v[30:31], v[30:31], v[232:233]
	v_exp_f32_e32 v248, v248
	v_pk_mul_f32 v[20:21], v[20:21], v[234:235]
	v_exp_f32_e32 v249, v249
	v_pk_mul_f32 v[22:23], v[22:23], v[236:237]
	v_exp_f32_e32 v250, v250
	v_pk_mul_f32 v[28:29], v[28:29], v[24:25]
	v_exp_f32_e32 v251, v251
	v_pk_mul_f32 v[30:31], v[30:31], v[26:27]
	v_exp_f32_e32 v252, v252
	v_pk_mul_f32 v[20:21], v[20:21], v[16:17]
	v_exp_f32_e32 v253, v253
	v_pk_mul_f32 v[22:23], v[22:23], v[18:19]
	v_pk_add_f32 v[246:247], v[246:247], 1.0 op_sel_hi:[1,0]
	v_cvt_pk_bf16_f32 v238, v28, v29
	v_pk_add_f32 v[248:249], v[248:249], 1.0 op_sel_hi:[1,0]
	v_cvt_pk_bf16_f32 v239, v30, v31
	v_pk_add_f32 v[250:251], v[250:251], 1.0 op_sel_hi:[1,0]
	v_cvt_pk_bf16_f32 v240, v20, v21
	v_pk_add_f32 v[252:253], v[252:253], 1.0 op_sel_hi:[1,0]
	v_cvt_pk_bf16_f32 v241, v22, v23
	s_add_u32 s88, s8, 0xdc000
	s_addc_u32 s89, s9, 0
	global_store_dwordx4 v229, v[238:241], s[88:89]
	v_rcp_f32_e32 v246, v246
	v_rcp_f32_e32 v247, v247
	v_rcp_f32_e32 v248, v248
	v_rcp_f32_e32 v249, v249
	v_rcp_f32_e32 v250, v250
	v_rcp_f32_e32 v251, v251
	v_rcp_f32_e32 v252, v252
	v_rcp_f32_e32 v253, v253
	v_pk_mul_f32 v[12:13], v[12:13], v[246:247]
	v_pk_mul_f32 v[14:15], v[14:15], v[248:249]
	v_pk_mul_f32 v[4:5], v[4:5], v[250:251]
	v_pk_mul_f32 v[6:7], v[6:7], v[252:253]
	v_pk_mul_f32 v[12:13], v[12:13], v[8:9]
	v_pk_mul_f32 v[14:15], v[14:15], v[10:11]
	v_pk_mul_f32 v[4:5], v[4:5], v[0:1]
	v_pk_mul_f32 v[6:7], v[6:7], v[2:3]
	v_cvt_pk_bf16_f32 v242, v12, v13
	v_cvt_pk_bf16_f32 v243, v14, v15
	v_cvt_pk_bf16_f32 v244, v4, v5
	v_cvt_pk_bf16_f32 v245, v6, v7
	s_add_u32 s88, s8, 0xf2000
	s_addc_u32 s89, s9, 0
	global_store_dwordx4 v229, v[242:245], s[88:89]
	s_cbranch_vccnz .LBB0_1338
	s_andn2_b64 vcc, exec, s[6:7]
	s_cbranch_vccnz .LBB0_1337
	s_barrier
	s_branch .LBB0_1337
